# speedup vs baseline: 1.0076x; 1.0019x over previous
; #define SBAR() __builtin_amdgcn_sched_barrier(0)
; #define SLOAD(k0) do { sv0 = *reinterpret_cast<const bf16x8*>(Vp + (k0) * LDV); sv1 = *reinterpret_cast<const bf16x8*>(Vp + ((k0) + 32) * LDV); \
;     sk0 = *reinterpret_cast<const bf16x8*>(Kp + (k0) * LDK); sk1 = *reinterpret_cast<const bf16x8*>(Kp + ((k0) + 32) * LDK); \
;     if constexpr (DQK == 192) sk2 = *reinterpret_cast<const bf16x8*>(Kp2 + (k0) * LDK); } while (0)
; #define SWRITE(KB, VB) do { *(bf16x8*)(V_lds + (VB) * SHM_V + vst0) = sv0; *(bf16x8*)(V_lds + (VB) * SHM_V + vst1) = sv1; \
;     *(bf16x8*)(K_lds + (KB) * SHM_K + kst0) = sk0; *(bf16x8*)(K_lds + (KB) * SHM_K + kst1) = sk1; } while (0)
; #define SLOAD(TILE) do { sv = *reinterpret_cast<const u32x4*>(Vp + (TILE) * 8192); sk0 = *reinterpret_cast<const u32x4*>(Kp0 + (TILE) * (64 * 3072)); \
;     if (two) sk1 = *reinterpret_cast<const u32x4*>(Kp1 + (TILE) * (64 * 3072)); } while (0)
; #define SWRITE(KB, VB) do { *(u32x4*)(V_lds + (VB) * SHM_V8 + vst) = sv; *(u32x4*)(K_lds + (KB) * SHM_K8 + kst0) = sk0; \
;     if (two) *(u32x4*)(K_lds + (KB) * SHM_K8 + kst1) = sk1; } while (0)
; __device__ __forceinline__ void qkt8(f32x16& p0, f32x16& p1, const char* Ks, const i32x8* qf, int r32, int hi) {
;   p0 = f32x16{}; p1 = f32x16{};
;   const char* kb = Ks + r32 * K8ROW + hi * 32;
;   i32x8 a0 = ld32B(kb), a1 = ld32B(kb + 32 * K8ROW);
;   i32x8 b0 = ld32B(kb + 64), b1 = ld32B(kb + 32 * K8ROW + 64);
; __device__ __forceinline__ void attn_body8(const bf16* __restrict__ Qb, const unsigned char* __restrict__ Kg, const unsigned char* __restrict__ Vg, ...
;     ...
;     __syncthreads();
;     if (j + 2 < NT) SWRITE((k4 + 2) & 3, VP2());
;     if (j + 3 < NT) SLOAD(j + 3);
;     SBAR(); qkt8(pB0, pB1, K_lds + k4 * SHM_K8, qf, r32, hi);
;     finishSM8(pA0, pA1, pf); SBAR();
.LBB0_906:
	s_cmp_gt_i32 s21, 2
	s_cselect_b32 s2, -3, 2
	s_add_i32 s2, s2, s21
	s_mulk_i32 s2, 0x2800
	s_xor_b32 s19, s22, 2
	v_add_u32_e32 v254, s2, v161
	s_mul_i32 s2, s19, 0x3400
	s_add_i32 s20, s2, 0
	s_barrier
	s_mul_i32 s2, s22, 0x3400
	v_add_u32_e32 v113, s2, v214
	ds_read_b128 v[80:83], v113 offset:51200
	ds_read_b128 v[84:87], v113 offset:51216
	s_waitcnt lgkmcnt(0)
	v_mfma_scale_f32_32x32x64_f8f6f4 v[96:111], v[80:87], v[120:127], 0, v193, v193 op_sel_hi:[0,0,0]
	ds_read_b128 v[80:83], v113 offset:57856
	ds_read_b128 v[84:87], v113 offset:57872
	ds_read_b128 v[218:221], v113 offset:51264
	ds_read_b128 v[222:225], v113 offset:51280
	s_waitcnt lgkmcnt(2)
	v_mfma_scale_f32_32x32x64_f8f6f4 v[80:95], v[80:87], v[120:127], 0, v193, v193 op_sel_hi:[0,0,0]
	s_waitcnt lgkmcnt(0)
	v_mfma_scale_f32_32x32x64_f8f6f4 v[96:111], v[218:225], v[128:135], v[96:111], v193, v193 op_sel_hi:[0,0,0]
	ds_read_b128 v[218:221], v113 offset:57920
	ds_read_b128 v[222:225], v113 offset:57936
	ds_read_b128 v[226:229], v113 offset:51328
	ds_read_b128 v[230:233], v113 offset:51344
	ds_read_b128 v[234:237], v113 offset:57984
	ds_read_b128 v[238:241], v113 offset:58000
	s_waitcnt vmcnt(1)
	ds_write_b128 v254, v[150:153]
	v_add_u32_e32 v254, s20, v158
	s_waitcnt vmcnt(0)
	ds_write_b128 v254, v[154:157] offset:51200
	s_and_saveexec_b64 s[10:11], s[6:7]
	v_add_u32_e32 v254, s20, v160
	ds_write_b128 v254, v[146:149] offset:51200
	s_or_b64 exec, exec, s[10:11]
	s_cmpk_lt_u32 s18, 0xfd
	s_cselect_b64 s[14:15], -1, 0
	s_cmpk_gt_u32 s18, 0xfc
	s_cselect_b64 s[12:13], -1, 0
	s_and_b64 vcc, exec, s[12:13]
	s_cbranch_vccnz .LMLA_noload
	global_load_dwordx4 v[150:153], v166, s[98:99]
	global_load_dwordx4 v[154:157], v252, s[100:101]
	s_and_saveexec_b64 s[10:11], s[6:7]
	s_cbranch_execz .LBB0_911
	global_load_dwordx4 v[146:149], v253, s[100:101]

; __device__ __forceinline__ void qkt8(f32x16& p0, f32x16& p1, const char* Ks, const i32x8* qf, int r32, int hi) {
;     ...
;   p0 = mfma8(b0, qf[1], p0); p1 = mfma8(b1, qf[1], p1);
;   p0 = mfma8(a0, qf[2], p0); p1 = mfma8(a1, qf[2], p1);
; }
; __device__ __forceinline__ void pv8(f32x16* o, f32x16& lacc, const char* Vs, i32x8 pf, int r32, int hi) {
;   const char* vb = Vs + r32 * V8ROW + hi * 32;
; #pragma unroll
;   for (int d0 = 0; d0 < 4; ++d0) o[d0] = mfma8(pf, ld32B(vb + d0 * 32 * V8ROW), o[d0]);
;   const int one4 = 0x38383838;
;   lacc = mfma8(pf, i32x8{one4, one4, one4, one4, one4, one4, one4, one4}, lacc);
; }
; __device__ __forceinline__ void partialSM8(f32x16& p0, f32x16& p1, float& m_reg, float& mn, float& alpha) {
;   float pmax = p0[0];
; #pragma unroll
;   for (int r = 1; r < 16; ++r) pmax = fmaxf(pmax, p0[r]);
; #pragma unroll
;   for (int r = 0; r < 16; ++r) pmax = fmaxf(pmax, p1[r]);
;   { auto rr = __builtin_amdgcn_permlane32_swap(__float_as_uint(pmax), __float_as_uint(pmax), false, false);
;     pmax = fmaxf(__uint_as_float(rr[0]), __uint_as_float(rr[1])); }
;   if (__builtin_expect(__all(pmax - m_reg <= THR8 * 8.f * 1.4426950408889634f), 1)) { mn = m_reg; alpha = 1.f; }
;   else { mn = fmaxf(m_reg, pmax); alpha = __builtin_amdgcn_exp2f((m_reg - mn) * 0.125f); m_reg = mn; }
;   const float mn8 = (P8SHIFT + 7.f - 0.0436f) * 8.f + 0.5f - mn;
; #pragma unroll
;   for (int r = 0; r < 16; ++r) p0[r] += mn8;
; #pragma unroll
;   for (int r = 0; r < 16; ++r) p1[r] += mn8;
; }
; __device__ __forceinline__ unsigned pk4u8(float a, float b, float c, float d) {
;   unsigned w = __builtin_amdgcn_cvt_pk_u8_f32(a, 0u, 0u); w = __builtin_amdgcn_cvt_pk_u8_f32(b, 1u, w);
;   w = __builtin_amdgcn_cvt_pk_u8_f32(c, 2u, w); return __builtin_amdgcn_cvt_pk_u8_f32(d, 3u, w);
; }
; __device__ __forceinline__ void finishSM8(f32x16& p0, f32x16& p1, i32x8& pf) {
; #pragma unroll
;   for (int w = 0; w < 4; ++w) { pf[w] = (int)pk4u8(p0[4 * w], p0[4 * w + 1], p0[4 * w + 2], p0[4 * w + 3]);
;                                 pf[4 + w] = (int)pk4u8(p1[4 * w], p1[4 * w + 1], p1[4 * w + 2], p1[4 * w + 3]); }
.LMLA_noload:
	v_cvt_pk_u8_f32 v113, v184, 0, 0
	v_cvt_pk_u8_f32 v113, v185, 1, v113
	v_cvt_pk_u8_f32 v113, v182, 2, v113
	s_waitcnt lgkmcnt(6)
	v_mfma_scale_f32_32x32x64_f8f6f4 v[80:95], v[218:225], v[128:135], v[80:95], v193, v193 op_sel_hi:[0,0,0]
	v_cvt_pk_u8_f32 v218, v183, 3, v113
	v_cvt_pk_u8_f32 v113, v198, 0, 0
	v_cvt_pk_u8_f32 v113, v199, 1, v113
	v_cvt_pk_u8_f32 v113, v196, 2, v113
	v_cvt_pk_u8_f32 v222, v197, 3, v113
	v_cvt_pk_u8_f32 v113, v178, 0, 0
	v_cvt_pk_u8_f32 v113, v179, 1, v113
	v_cvt_pk_u8_f32 v113, v174, 2, v113
	v_cvt_pk_u8_f32 v219, v175, 3, v113
	v_cvt_pk_u8_f32 v113, v194, 0, 0
	v_cvt_pk_u8_f32 v113, v195, 1, v113
	v_cvt_pk_u8_f32 v113, v190, 2, v113
	v_cvt_pk_u8_f32 v223, v191, 3, v113
	v_cvt_pk_u8_f32 v113, v172, 0, 0
	v_cvt_pk_u8_f32 v113, v173, 1, v113
	s_waitcnt lgkmcnt(4)
	v_mfma_scale_f32_32x32x64_f8f6f4 v[96:111], v[226:233], v[136:143], v[96:111], v193, v193 op_sel_hi:[0,0,0]
	v_cvt_pk_u8_f32 v113, v118, 2, v113
	v_cvt_pk_u8_f32 v220, v119, 3, v113
	v_cvt_pk_u8_f32 v113, v188, 0, 0
	v_cvt_pk_u8_f32 v113, v189, 1, v113
	v_cvt_pk_u8_f32 v113, v186, 2, v113
	v_cvt_pk_u8_f32 v224, v187, 3, v113
	v_cvt_pk_u8_f32 v113, v116, 0, 0
	v_cvt_pk_u8_f32 v113, v117, 1, v113
	v_cvt_pk_u8_f32 v113, v114, 2, v113
	v_cvt_pk_u8_f32 v221, v115, 3, v113
	v_cvt_pk_u8_f32 v113, v180, 0, 0
	v_cvt_pk_u8_f32 v113, v181, 1, v113
	v_cvt_pk_u8_f32 v113, v176, 2, v113
	v_cvt_pk_u8_f32 v225, v177, 3, v113
	s_waitcnt lgkmcnt(0)
	v_mfma_scale_f32_32x32x64_f8f6f4 v[80:95], v[234:241], v[136:143], v[80:95], v193, v193 op_sel_hi:[0,0,0]
	s_mul_i32 s2, s21, 0x2800
	s_addk_i32 s2, 0xd800
	s_cmp_lg_u32 s21, 0
	s_cselect_b32 s2, s2, 0xa000
	v_add_u32_e32 v113, s2, v217
	ds_read_b128 v[172:175], v113
	ds_read_b128 v[176:179], v113 offset:16
	v_max_f32_e32 v188, v97, v97
	v_max_f32_e32 v189, v96, v96
	v_max_f32_e32 v188, v189, v188
	v_max3_f32 v188, v188, v98, v99
	s_waitcnt lgkmcnt(0)
	v_mfma_scale_f32_32x32x64_f8f6f4 v[48:63], v[218:225], v[172:179], v[48:63], v193, v193 op_sel_hi:[0,0,0]
	ds_read_b128 v[172:175], v113 offset:2560
	ds_read_b128 v[176:179], v113 offset:2576
	s_waitcnt lgkmcnt(0)
	v_mfma_scale_f32_32x32x64_f8f6f4 v[32:47], v[218:225], v[172:179], v[32:47], v193, v193 op_sel_hi:[0,0,0]
	ds_read_b128 v[172:175], v113 offset:5120
	ds_read_b128 v[176:179], v113 offset:5136
	ds_read_b128 v[180:183], v113 offset:7680
	ds_read_b128 v[184:187], v113 offset:7696
	s_waitcnt lgkmcnt(2)
	v_mfma_scale_f32_32x32x64_f8f6f4 v[16:31], v[218:225], v[172:179], v[16:31], v193, v193 op_sel_hi:[0,0,0]
	v_max3_f32 v172, v188, v100, v101
	v_max3_f32 v172, v172, v102, v103
	v_max3_f32 v172, v172, v104, v105
	v_max3_f32 v172, v172, v106, v107
	v_max3_f32 v172, v172, v108, v109
	v_max3_f32 v172, v172, v110, v111
	v_max3_f32 v172, v172, v80, v81
	v_max3_f32 v172, v172, v82, v83
	v_max3_f32 v172, v172, v84, v85
	v_max3_f32 v172, v172, v86, v87
	v_max3_f32 v172, v172, v88, v89
	v_max3_f32 v172, v172, v90, v91
	v_max3_f32 v172, v172, v92, v93
	v_max3_f32 v172, v172, v94, v95
	v_mov_b32_e32 v173, v172
	s_waitcnt lgkmcnt(0)
	v_mfma_scale_f32_32x32x64_f8f6f4 v[0:15], v[218:225], v[180:187], v[0:15], v193, v193 op_sel_hi:[0,0,0]
	v_permlane32_swap_b32_e32 v172, v173
	v_max_f32_e32 v172, v172, v173
	v_sub_f32_e32 v173, v172, v216
	v_cmp_ge_f32_e32 vcc, s61, v173
	v_mfma_scale_f32_16x16x128_f8f6f4 v[64:67], v[218:225], v[244:251], v[64:67], v193, v193 op_sel_hi:[0,0,0]
	s_cmp_eq_u64 vcc, exec
	s_cselect_b64 s[10:11], -1, 0
	s_cbranch_scc1 .LBB0_916
	v_max_f32_e32 v172, v216, v172
	v_sub_f32_e32 v174, v216, v172
	v_mul_f32_e32 v174, 0x3e000000, v174
	v_exp_f32_e32 v174, v174
	s_nop 0
	v_mov_b32_e32 v173, v174
	v_cmp_gt_f32_e32 vcc, 1.0, v173
	s_cbranch_vccz .LBB0_916
	s_and_saveexec_b64 s[16:17], s[8:9]
	ds_write_b32 v215, v173 offset:128
	s_or_b64 exec, exec, s[16:17]
	s_waitcnt lgkmcnt(0)
	v_add_u32_e32 v113, v159, v213
	ds_read_b128 v[114:117], v113 offset:224
	ds_read_b128 v[174:177], v113 offset:192
	ds_read_b128 v[178:181], v113 offset:160
	ds_read_b128 v[182:185], v113 offset:128
	s_waitcnt lgkmcnt(3)
	v_pk_mul_f32 v[60:61], v[60:61], v[114:115]
	s_waitcnt lgkmcnt(2)
	v_pk_mul_f32 v[56:57], v[56:57], v[174:175]
	s_waitcnt lgkmcnt(1)
	v_pk_mul_f32 v[52:53], v[52:53], v[178:179]
	v_pk_mul_f32 v[62:63], v[62:63], v[116:117]
	v_pk_mul_f32 v[58:59], v[58:59], v[176:177]
	v_pk_mul_f32 v[54:55], v[54:55], v[180:181]
	s_waitcnt lgkmcnt(0)
	v_pk_mul_f32 v[50:51], v[50:51], v[184:185]
	v_pk_mul_f32 v[48:49], v[48:49], v[182:183]
	v_pk_mul_f32 v[44:45], v[44:45], v[114:115]
	v_pk_mul_f32 v[40:41], v[40:41], v[174:175]
	v_pk_mul_f32 v[36:37], v[36:37], v[178:179]
	v_pk_mul_f32 v[46:47], v[46:47], v[116:117]
	v_pk_mul_f32 v[42:43], v[42:43], v[176:177]
	v_pk_mul_f32 v[38:39], v[38:39], v[180:181]
	v_pk_mul_f32 v[34:35], v[34:35], v[184:185]
	v_pk_mul_f32 v[32:33], v[32:33], v[182:183]
	v_pk_mul_f32 v[28:29], v[28:29], v[114:115]
	v_pk_mul_f32 v[24:25], v[24:25], v[174:175]
	v_pk_mul_f32 v[20:21], v[20:21], v[178:179]
	v_pk_mul_f32 v[30:31], v[30:31], v[116:117]
	v_pk_mul_f32 v[26:27], v[26:27], v[176:177]
	v_pk_mul_f32 v[22:23], v[22:23], v[180:181]
	v_pk_mul_f32 v[18:19], v[18:19], v[184:185]
	v_pk_mul_f32 v[16:17], v[16:17], v[182:183]
	v_pk_mul_f32 v[12:13], v[12:13], v[114:115]
	v_pk_mul_f32 v[8:9], v[8:9], v[174:175]
	v_pk_mul_f32 v[4:5], v[4:5], v[178:179]
	v_pk_mul_f32 v[14:15], v[14:15], v[116:117]
	v_pk_mul_f32 v[10:11], v[10:11], v[176:177]
	v_pk_mul_f32 v[6:7], v[6:7], v[180:181]
	v_pk_mul_f32 v[2:3], v[2:3], v[184:185]
	v_pk_mul_f32 v[0:1], v[0:1], v[182:183]
	ds_read_b128 v[114:117], v242 offset:128
	s_waitcnt lgkmcnt(0)
	v_pk_mul_f32 v[64:65], v[64:65], v[114:115]
	v_pk_mul_f32 v[66:67], v[66:67], v[116:117]
